# stack6 + mix kinds 2-4: all eleven operand loads issued before the first counted wait (was a vmcnt(0) drain after three) + scan3 MFMA section: 18 fragment reads up front, four interleaved accumulate c
# speedup vs baseline: 1.0040x; 1.0040x over previous
; #define GAS __attribute__((address_space(1)))
; __device__ __forceinline__ void unpack8(const v4u w, float (&f)[8]) { f[0] = bf_lo(w.x); f[1] = bf_hi(w.x); f[2] = bf_lo(w.y); f[3] = bf_hi(w.y); f[4] = bf_lo(w.z); f[5] = bf_hi(w.z); f[6] = bf_lo(w.w); f[7] = bf_hi(w.w); }
; __device__ __forceinline__ void phase_mix(Frame& F, int l) {
;     ...
;             const int cl = (ch - 2) * 512 + lane * 8;
;             if (cl < DSHIFT) {
;                 v4u rc[9];
;                 const GAS bf16* pm1 = (t0 > 0) ? p0 - DIN : (samp ? P + (size_t)(M + b) * DIN : nullptr);
;                 if (pm1) rc[0] = *(const GAS v4u*)(pm1 + OFF_R + cl); else rc[0] = (v4u){0u, 0u, 0u, 0u};
; #pragma unroll
;                 for (int i = 0; i < 8; ++i) rc[i + 1] = *(const GAS v4u*)(p0 + (size_t)i * DIN + OFF_R + cl);
;                 float muv[8];
;                 { const f32x4 a0 = *(const GAS f32x4*)(mu + cl), a1 = *(const GAS f32x4*)(mu + cl + 4); muv[0] = a0.x; muv[1] = a0.y; muv[2] = a0.z; muv[3] = a0.w; muv[4] = a1.x; muv[5] = a1.y; muv[6] = a1.z; muv[7] = a1.w; }
;                 float prv[8]; unpack8(rc[0], prv);
; #pragma unroll
;                 for (int i = 0; i < 8; ++i) { float cur[8], mx[8]; unpack8(rc[i + 1], cur);
; #pragma unroll
;                     for (int j = 0; j < 8; ++j) { mx[j] = cur[j] + muv[j] * (prv[j] - cur[j]); prv[j] = cur[j]; }
.LBB0_349:
	v_lshlrev_b64 v[58:59], 1, v[60:61]
	v_lshl_add_u64 v[26:27], s[38:39], 0, v[58:59]
	v_add_co_u32_e32 v18, vcc, 0x1000, v26
	s_mov_b32 s6, 0x16000
	s_nop 0
	v_addc_co_u32_e32 v19, vcc, 0, v27, vcc
	v_add_co_u32_e32 v20, vcc, 0x6000, v26
	v_lshl_add_u64 v[22:23], v[60:61], 2, s[22:23]
	s_nop 0
	v_addc_co_u32_e32 v21, vcc, 0, v27, vcc
	global_load_dwordx4 v[68:71], v[18:19], off offset:2048
	global_load_dwordx4 v[50:53], v[20:21], off offset:2560
	v_add_co_u32_e32 v18, vcc, 0xb000, v26
	s_cmp_gt_u32 s10, 7
	s_nop 0
	v_addc_co_u32_e32 v19, vcc, 0, v27, vcc
	v_add_co_u32_e32 v20, vcc, s41, v26
	v_addc_co_u32_e32 v21, vcc, 0, v27, vcc
	global_load_dwordx4 v[46:49], v[18:19], off offset:3072
	global_load_dwordx4 v[42:45], v[20:21], off offset:3584
	v_add_co_u32_e32 v18, vcc, s6, v26
	s_movk_i32 s6, 0xc3f
	s_nop 0
	v_addc_co_u32_e32 v19, vcc, 0, v27, vcc
	v_add_co_u32_e32 v20, vcc, 0x1b000, v26
	v_cmp_lt_i32_e64 s[8:9], s6, v60
	s_nop 0
	v_addc_co_u32_e32 v21, vcc, 0, v27, vcc
	v_add_co_u32_e32 v28, vcc, 0x20000, v26
	global_load_dwordx4 v[38:41], v[18:19], off
	global_load_dwordx4 v[34:37], v[20:21], off offset:512
	v_addc_co_u32_e32 v29, vcc, 0, v27, vcc
	v_add_co_u32_e32 v26, vcc, 0x25000, v26
	global_load_dwordx4 v[18:21], v[22:23], off offset:16
	s_nop 0
	global_load_dwordx4 v[22:25], v[22:23], off
	v_addc_co_u32_e32 v27, vcc, 0, v27, vcc
	global_load_dwordx4 v[30:33], v[28:29], off offset:1024
	s_nop 0
	global_load_dwordx4 v[26:29], v[26:27], off offset:1536
	s_movk_i32 s6, 0xc7f
	v_cmp_lt_u32_e64 s[6:7], s6, v60
	s_waitcnt vmcnt(10)
	v_lshlrev_b32_e32 v66, 16, v54
	v_and_b32_e32 v67, 0xffff0000, v54
	v_lshlrev_b32_e32 v72, 16, v55
	v_and_b32_e32 v73, 0xffff0000, v55
	v_lshlrev_b32_e32 v74, 16, v56
	v_and_b32_e32 v75, 0xffff0000, v56
	v_lshlrev_b32_e32 v56, 16, v57
	v_and_b32_e32 v57, 0xffff0000, v57
	s_cselect_b64 s[64:65], -1, 0
	v_lshl_add_u64 v[54:55], s[20:21], 0, v[58:59]
	s_mov_b64 s[10:11], -1
	s_and_b64 vcc, exec, s[64:65]
	s_waitcnt vmcnt(9)
	v_lshlrev_b32_e32 v64, 16, v68
	v_and_b32_e32 v65, 0xffff0000, v68
	v_lshlrev_b32_e32 v68, 16, v69
	v_and_b32_e32 v69, 0xffff0000, v69
	v_lshlrev_b32_e32 v62, 16, v70
	v_and_b32_e32 v63, 0xffff0000, v70
	v_lshlrev_b32_e32 v60, 16, v71
	v_and_b32_e32 v61, 0xffff0000, v71
	v_pk_add_f32 v[66:67], v[66:67], v[64:65] neg_lo:[0,1] neg_hi:[0,1]
	v_pk_add_f32 v[70:71], v[72:73], v[68:69] neg_lo:[0,1] neg_hi:[0,1]
	v_pk_add_f32 v[72:73], v[74:75], v[62:63] neg_lo:[0,1] neg_hi:[0,1]
	v_pk_add_f32 v[56:57], v[56:57], v[60:61] neg_lo:[0,1] neg_hi:[0,1]
	s_waitcnt vmcnt(3)
	v_pk_fma_f32 v[72:73], v[72:73], v[18:19], v[62:63]
	s_waitcnt vmcnt(2)
	v_pk_fma_f32 v[66:67], v[66:67], v[22:23], v[64:65]
	v_pk_fma_f32 v[70:71], v[70:71], v[24:25], v[68:69]
	v_pk_fma_f32 v[74:75], v[56:57], v[20:21], v[60:61]
	s_cbranch_vccz .LBB0_357
	s_and_saveexec_b64 s[10:11], s[8:9]
	s_xor_b64 s[10:11], exec, s[10:11]
	s_cbranch_execz .LBB0_354
	v_mov_b32_e32 v81, v75
	v_mov_b32_e32 v80, v74
	v_mov_b32_e32 v79, v73
	v_mov_b32_e32 v78, v72
	v_mov_b32_e32 v77, v71
	v_mov_b32_e32 v76, v70
	v_mov_b32_e32 v57, v67
	v_mov_b32_e32 v56, v66
	s_and_saveexec_b64 vcc, s[6:7]
	s_cbranch_execz .LBB0_353
	v_mul_f32_e32 v56, 0xbfb8aa3b, v66
	v_mul_f32_e32 v57, 0xbfb8aa3b, v67
	v_mul_f32_e32 v76, 0xbfb8aa3b, v70
	v_mul_f32_e32 v77, 0xbfb8aa3b, v71
	v_mul_f32_e32 v78, 0xbfb8aa3b, v72
	v_mul_f32_e32 v79, 0xbfb8aa3b, v73
	v_mul_f32_e32 v80, 0xbfb8aa3b, v74
	v_mul_f32_e32 v81, 0xbfb8aa3b, v75
	v_exp_f32_e32 v56, v56
	v_exp_f32_e32 v57, v57
	v_exp_f32_e32 v76, v76
	v_exp_f32_e32 v77, v77
	v_exp_f32_e32 v78, v78
	v_exp_f32_e32 v79, v79
	v_exp_f32_e32 v80, v80
	v_exp_f32_e32 v81, v81
	v_add_f32_e32 v56, 1.0, v56
	v_add_f32_e32 v57, 1.0, v57
	v_add_f32_e32 v76, 1.0, v76
	v_add_f32_e32 v77, 1.0, v77
	v_add_f32_e32 v78, 1.0, v78
	v_add_f32_e32 v79, 1.0, v79
	v_add_f32_e32 v80, 1.0, v80
	v_add_f32_e32 v81, 1.0, v81
	v_rcp_f32_e32 v56, v56
	v_rcp_f32_e32 v57, v57
	v_rcp_f32_e32 v76, v76
	v_rcp_f32_e32 v77, v77
	v_rcp_f32_e32 v78, v78
	v_rcp_f32_e32 v79, v79
	v_rcp_f32_e32 v80, v80
	v_rcp_f32_e32 v81, v81

; __device__ __forceinline__ void phase_scan3(Frame& F, int l) {
;     ...
;         {   bf16x8 a_[2];
; #pragma unroll
;             for (int ks = 0; ks < 2; ++ks) a_[ks] = frag(QH, tm, ks, lane);
; #pragma unroll
;             for (int q = 0; q < 2; ++q) { const int tn = tn0 + q; f32x4 acc = {0.f, 0.f, 0.f, 0.f};
; #pragma unroll
;                 for (int ks = 0; ks < 2; ++ks) acc = mma16(frag(SCB, tn, ks, lane), a_[ks], acc);
;                 *(LAS f32x4*)(YF + (16 * tm + fr) * YP + 16 * tn + 4 * fq) = acc; }
;             bf16x8 x_[4];
; #pragma unroll
;             for (int ks = 0; ks < 4; ++ks) x_[ks] = *(const LAS bf16x8*)(XG + (16 * tm + fr) * GP + 32 * ks + 8 * fq);
; #pragma unroll
;             for (int q = 0; q < 2; ++q) { const int tn = tn0 + q; f32x4 acc = {0.f, 0.f, 0.f, 0.f};
; #pragma unroll
;                 for (int ks = 0; ks < 4; ++ks) acc = mma16(*(const LAS bf16x8*)(WG + (16 * tn + fr) * GP + 32 * ks + 8 * fq), x_[ks], acc);
;                 *(LAS f32x4*)(GF + (16 * tm + fr) * YP + 16 * tn + 4 * fq) = acc; }
;         }
;         lds_barrier();
;         {   float y[8], y0[8], vv[8], g[8], ov[8]; unpack8(y0w, y0); unpack8(vw, vv);
;             { const f32x4 ga = *(const LAS f32x4*)(GF + tok * YP + sg * 8), gb = *(const LAS f32x4*)(GF + tok * YP + sg * 8 + 4); g[0] = ga[0]; g[1] = ga[1]; g[2] = ga[2]; g[3] = ga[3]; g[4] = gb[0]; g[5] = gb[1]; g[6] = gb[2]; g[7] = gb[3]; }
;             const f32x4 ya = *(const LAS f32x4*)(YF + tok * YP + sg * 8), yb = *(const LAS f32x4*)(YF + tok * YP + sg * 8 + 4);
;             y[0] = ya[0] + y0[0]; y[1] = ya[1] + y0[1]; y[2] = ya[2] + y0[2]; y[3] = ya[3] + y0[3]; y[4] = yb[0] + y0[4]; y[5] = yb[1] + y0[5]; y[6] = yb[2] + y0[6]; y[7] = yb[3] + y0[7];
;             float s_ = 0.f;
; #pragma unroll
;             for (int j = 0; j < 8; ++j) s_ += y[j];
;             const float mean = sum8(s_) * (1.f / 64.f); float qv = 0.f;
; #pragma unroll
;             for (int j = 0; j < 8; ++j) { y[j] -= mean; qv += y[j] * y[j]; }
;             const float rstd = __builtin_amdgcn_rsqf(sum8(qv) * (1.f / 64.f) + GN_EPS);
; #pragma unroll
;             for (int j = 0; j < 8; ++j) { const float lw_ = (j < 4) ? lw0[j & 3] : lw1[j & 3], lb_ = (j < 4) ? lb0[j & 3] : lb1[j & 3]; ov[j] = (y[j] * rstd * lw_ + lb_ + bon * vv[j]) * g[j]; }
;             *(GAS v4u*)(ARWKV + m * DC + col) = pack8(ov);
.LBB0_768:
	ds_read_b128 v[84:87], v62
	ds_read_b128 v[92:95], v78 offset:9216
	ds_read_b128 v[108:111], v79 offset:9216
	ds_read_b128 v[88:91], v62 offset:64
	ds_read_b128 v[96:99], v78 offset:9280
	ds_read_b128 v[112:115], v79 offset:9280
	ds_read_b128 v[116:119], v63 offset:35840
	ds_read_b128 v[132:135], v80 offset:53248
	ds_read_b128 v[148:151], v81 offset:53248
	ds_read_b128 v[120:123], v63 offset:35904
	ds_read_b128 v[136:139], v80 offset:53312
	ds_read_b128 v[152:155], v81 offset:53312
	ds_read_b128 v[124:127], v63 offset:35968
	ds_read_b128 v[140:143], v80 offset:53376
	ds_read_b128 v[156:159], v81 offset:53376
	ds_read_b128 v[128:131], v63 offset:36032
	ds_read_b128 v[144:147], v80 offset:53440
	ds_read_b128 v[160:163], v81 offset:53440
	v_add_u32_e32 v180, s82, v63
	v_add_u32_e32 v181, s83, v63
	v_add_u32_e32 v182, s82, v75
	v_add_u32_e32 v0, s83, v75
	v_add_u32_e32 v70, s22, v58
	v_ashrrev_i32_e32 v71, 31, v70
	s_add_i32 s1, s1, s77
	s_add_i32 s0, s0, s84
	s_andn2_b64 vcc, exec, s[18:19]
	v_lshlrev_b32_e32 v100, 16, v37
	v_and_b32_e32 v101, 0xffff0000, v37
	v_lshlrev_b32_e32 v102, 16, v41
	v_and_b32_e32 v103, 0xffff0000, v41
	v_and_b32_e32 v37, 0xffff0000, v40
	s_waitcnt lgkmcnt(15)
	v_mfma_f32_16x16x32_bf16 v[164:167], v[92:95], v[84:87], 0
	v_mfma_f32_16x16x32_bf16 v[168:171], v[108:111], v[84:87], 0
	s_waitcnt lgkmcnt(13)
	v_mfma_f32_16x16x32_bf16 v[164:167], v[96:99], v[88:91], v[164:167]
	s_waitcnt lgkmcnt(12)
	v_mfma_f32_16x16x32_bf16 v[168:171], v[112:115], v[88:91], v[168:171]
	s_waitcnt lgkmcnt(10)
	v_mfma_f32_16x16x32_bf16 v[172:175], v[132:135], v[116:119], 0
	s_waitcnt lgkmcnt(9)
	v_mfma_f32_16x16x32_bf16 v[176:179], v[148:151], v[116:119], 0
	s_waitcnt lgkmcnt(7)
	v_mfma_f32_16x16x32_bf16 v[172:175], v[136:139], v[120:123], v[172:175]
	s_waitcnt lgkmcnt(6)
	v_mfma_f32_16x16x32_bf16 v[176:179], v[152:155], v[120:123], v[176:179]
	s_waitcnt lgkmcnt(4)
	v_mfma_f32_16x16x32_bf16 v[172:175], v[140:143], v[124:127], v[172:175]
	s_waitcnt lgkmcnt(3)
	v_mfma_f32_16x16x32_bf16 v[176:179], v[156:159], v[124:127], v[176:179]
	s_waitcnt lgkmcnt(1)
	v_mfma_f32_16x16x32_bf16 v[172:175], v[144:147], v[128:131], v[172:175]
	s_waitcnt lgkmcnt(0)
	v_mfma_f32_16x16x32_bf16 v[176:179], v[160:163], v[128:131], v[176:179]
	ds_write_b128 v180, v[164:167] offset:18432
	ds_write_b128 v181, v[168:171] offset:18432
	s_nop 6
	ds_write_b128 v182, v[172:175]
	s_nop 0
	ds_write_b128 v0, v[176:179]
	s_waitcnt lgkmcnt(0)
	s_barrier
	ds_read_b128 v[84:87], v76
	ds_read_b128 v[88:91], v76 offset:16
	ds_read_b128 v[92:95], v77 offset:18432
	ds_read_b128 v[96:99], v77 offset:18448
	s_waitcnt lgkmcnt(0)
	v_pk_add_f32 v[98:99], v[98:99], v[100:101]
	v_lshlrev_b32_e32 v100, 16, v36
	v_and_b32_e32 v101, 0xffff0000, v36
	v_lshlrev_b32_e32 v36, 16, v40
	v_pk_add_f32 v[40:41], v[96:97], v[100:101]
	v_lshlrev_b32_e32 v96, 16, v35
	v_and_b32_e32 v97, 0xffff0000, v35
	v_pk_add_f32 v[94:95], v[94:95], v[96:97]
	v_lshlrev_b32_e32 v96, 16, v34
	v_and_b32_e32 v97, 0xffff0000, v34
	v_lshlrev_b32_e32 v100, 16, v39
	v_and_b32_e32 v101, 0xffff0000, v39
	v_lshlrev_b32_e32 v34, 16, v38
	v_and_b32_e32 v35, 0xffff0000, v38
	v_pk_add_f32 v[38:39], v[92:93], v[96:97]
	s_nop 0
	v_add_f32_e32 v0, 0, v38
	v_add_f32_e32 v0, v39, v0
	v_add_f32_e32 v0, v94, v0
	v_add_f32_e32 v0, v95, v0
	v_add_f32_e32 v0, v40, v0
	v_add_f32_e32 v0, v41, v0
	v_add_f32_e32 v0, v98, v0
	v_add_f32_e32 v0, v99, v0
	s_nop 1
	v_add_f32_dpp v0, v0, v0 quad_perm:[1,0,3,2] row_mask:0xf bank_mask:0xf bound_ctrl:1
	s_nop 1
	v_add_f32_dpp v0, v0, v0 quad_perm:[2,3,0,1] row_mask:0xf bank_mask:0xf bound_ctrl:1
	s_nop 1
	v_add_f32_dpp v0, v0, v0 row_half_mirror row_mask:0xf bank_mask:0xf bound_ctrl:1
	v_mul_f32_e32 v0, 0x3c800000, v0
	v_pk_add_f32 v[38:39], v[38:39], v[0:1] op_sel_hi:[1,0] neg_lo:[0,1] neg_hi:[0,1]
	v_pk_add_f32 v[94:95], v[94:95], v[0:1] op_sel_hi:[1,0] neg_lo:[0,1] neg_hi:[0,1]
	v_pk_mul_f32 v[92:93], v[38:39], v[38:39]
	v_pk_mul_f32 v[96:97], v[94:95], v[94:95]
	v_pk_add_f32 v[40:41], v[40:41], v[0:1] op_sel_hi:[1,0] neg_lo:[0,1] neg_hi:[0,1]
	v_pk_add_f32 v[98:99], v[98:99], v[0:1] op_sel_hi:[1,0] neg_lo:[0,1] neg_hi:[0,1]
	v_add_f32_e32 v0, v92, v93
	v_add_f32_e32 v0, v96, v0
	v_pk_mul_f32 v[104:105], v[40:41], v[40:41]
	v_add_f32_e32 v0, v97, v0
	v_add_f32_e32 v0, v104, v0
	v_pk_mul_f32 v[106:107], v[98:99], v[98:99]
	v_add_f32_e32 v0, v105, v0
	v_add_f32_e32 v0, v106, v0
	v_add_f32_e32 v0, v107, v0
	v_mov_b32_e32 v92, 0x3a27c5ac
	s_nop 0
	v_add_f32_dpp v0, v0, v0 quad_perm:[1,0,3,2] row_mask:0xf bank_mask:0xf bound_ctrl:1
	s_nop 1
	v_add_f32_dpp v0, v0, v0 quad_perm:[2,3,0,1] row_mask:0xf bank_mask:0xf bound_ctrl:1
	s_nop 1
	v_add_f32_dpp v0, v0, v0 row_half_mirror row_mask:0xf bank_mask:0xf bound_ctrl:1
	v_fmamk_f32 v0, v0, 0x3c800000, v92
	v_rsq_f32_e32 v0, v0
	s_nop 0
	v_pk_mul_f32 v[38:39], v[38:39], v[0:1] op_sel_hi:[1,0]
	s_waitcnt vmcnt(0)
	v_pk_fma_f32 v[38:39], v[50:51], v[38:39], v[54:55]
	v_pk_mul_f32 v[40:41], v[40:41], v[0:1] op_sel_hi:[1,0]
	v_pk_fma_f32 v[34:35], v[68:69], v[34:35], v[38:39] op_sel_hi:[0,1,1]
	v_pk_mul_f32 v[38:39], v[94:95], v[0:1] op_sel_hi:[1,0]
	v_pk_fma_f32 v[40:41], v[42:43], v[40:41], v[46:47]
	v_pk_fma_f32 v[38:39], v[52:53], v[38:39], v[56:57]
	v_pk_fma_f32 v[36:37], v[68:69], v[36:37], v[40:41] op_sel_hi:[0,1,1]
	v_pk_fma_f32 v[38:39], v[68:69], v[100:101], v[38:39] op_sel_hi:[0,1,1]
	v_pk_mul_f32 v[40:41], v[98:99], v[0:1] op_sel_hi:[1,0]
	v_pk_mul_f32 v[34:35], v[84:85], v[34:35]
	v_pk_mul_f32 v[38:39], v[86:87], v[38:39]
	v_pk_fma_f32 v[40:41], v[44:45], v[40:41], v[48:49]
	v_cvt_pk_bf16_f32 v34, v34, v35
	v_pk_fma_f32 v[40:41], v[68:69], v[102:103], v[40:41] op_sel_hi:[0,1,1]
	v_cvt_pk_bf16_f32 v35, v38, v39
	v_lshlrev_b64 v[38:39], 11, v[70:71]
	v_pk_mul_f32 v[36:37], v[88:89], v[36:37]
	v_pk_mul_f32 v[40:41], v[90:91], v[40:41]
	v_lshl_add_u64 v[38:39], s[10:11], 0, v[38:39]
	v_lshlrev_b32_e32 v0, 1, v83
	v_cvt_pk_bf16_f32 v36, v36, v37
	v_cvt_pk_bf16_f32 v37, v40, v41
	v_lshl_add_u64 v[38:39], v[38:39], 0, v[0:1]
	global_store_dwordx4 v[38:39], v[34:37], off
	s_waitcnt lgkmcnt(0)
	s_barrier
	v_mov_b64_e32 v[40:41], v[32:33]
	v_mov_b64_e32 v[36:37], v[28:29]
	v_mov_b64_e32 v[34:35], v[26:27]
	v_mov_b64_e32 v[38:39], v[30:31]
	v_mov_b32_e32 v68, v82
	s_cbranch_vccz .LBB0_778
